# v24 + down-GEMM epilogue hand-written with all residual rows requested up front
# speedup vs baseline: 1.0058x; 1.0058x over previous
; __device__ __forceinline__ u32x4 pack8(const f32x4 a, const f32x4 b) { u32x4 w; w.x = cvt_pk_bf16(a[0], a[1]); w.y = cvt_pk_bf16(a[2], a[3]); w.z = cvt_pk_bf16(b[0], b[1]); w.w = cvt_pk_bf16(b[2], b[3]); return w; }
;     __device__ __forceinline__ void operator()(const f32x4 (&acc)[2][2][4][2], const pg8::Unit& u, int wr, int wc, int fr, int fq) const {
;     ...
; #pragma unroll
;         for (int ai = 0; ai < 2; ++ai) {
;             u32x4 hr[4][2]; float q1v[4];
; #pragma unroll
;             for (int m = 0; m < 4; ++m) { q1v[m] = rss1[row0 + ai * 128 + m * 16];
; #pragma unroll
;                 for (int bj = 0; bj < 2; ++bj) hr[m][bj] = *(const u32x4*)(HB + (size_t)(row0 + ai * 128 + m * 16) * DM + col0 + bj * 128); }
; #pragma unroll
;             for (int m = 0; m < 4; ++m) { const float iq = (127.f / QCLIP) * rsqrtf(q1v[m] * (1.f / DM) + EPS);
; #pragma unroll
;                 for (int bj = 0; bj < 2; ++bj) { float hv[8]; unpack8(hr[m][bj], hv); const size_t off = (size_t)(row0 + ai * 128 + m * 16) * DM + col0 + bj * 128;
;                     f32x4 h0 = acc[ai][bj][m][0], h1 = acc[ai][bj][m][1];
; #pragma unroll
;                     for (int e = 0; e < 4; ++e) { h0[e] += hv[e]; h1[e] += hv[4 + e]; }
;                     *(u32x4*)(HB + off) = pack8(h0, h1);
;                     f32x4 q0, q1;
; #pragma unroll
;                     for (int ee = 0; ee < 4; ++ee) { q0[ee] = fminf(fmaxf(rintf(h0[ee] * iq), -127.f), 127.f); q1[ee] = fminf(fmaxf(rintf(h1[ee] * iq), -127.f), 127.f); }
;                     *(u32x2*)(HQ + off) = pack8_i8(q0, q1); } }
;             asm volatile("" ::: "memory"); }
;     }
.LBB0_1379:
	s_mov_b32 s98, s1
	s_mov_b32 s99, s4
	v_lshlrev_b32_e32 v250, 2, v1
	v_lshlrev_b32_e32 v251, 13, v1
	v_lshlrev_b32_e32 v252, 12, v1
	v_lshl_add_u32 v251, v181, 1, v251
	v_add_u32_e32 v252, v252, v181
	s_lshl_b32 s26, s98, 10
	s_add_u32 s28, s18, s26
	s_addc_u32 s29, s19, 0
	s_lshl_b32 s26, s98, 21
	s_lshl_b32 s27, s99, 9
	s_add_u32 s26, s26, s27
	s_add_u32 s84, s14, s26
	s_addc_u32 s85, s15, 0
	s_mov_b64 s[86:87], s[84:85]
	s_lshr_b32 s27, s26, 1
	s_add_u32 s88, s16, s27
	s_addc_u32 s89, s17, 0
	global_load_dword v162, v250, s[28:29]
	global_load_dwordx4 v[188:191], v251, s[84:85]
	global_load_dwordx4 v[192:195], v251, s[84:85] offset:256
	s_add_u32 s84, s84, 0x20000
	s_addc_u32 s85, s85, 0
	global_load_dword v163, v250, s[28:29] offset:64
	global_load_dwordx4 v[196:199], v251, s[84:85]
	global_load_dwordx4 v[200:203], v251, s[84:85] offset:256
	s_add_u32 s84, s84, 0x20000
	s_addc_u32 s85, s85, 0
	global_load_dword v164, v250, s[28:29] offset:128
	global_load_dwordx4 v[204:207], v251, s[84:85]
	global_load_dwordx4 v[208:211], v251, s[84:85] offset:256
	s_add_u32 s84, s84, 0x20000
	s_addc_u32 s85, s85, 0
	global_load_dword v165, v250, s[28:29] offset:192
	global_load_dwordx4 v[212:215], v251, s[84:85]
	global_load_dwordx4 v[216:219], v251, s[84:85] offset:256
	s_add_u32 s84, s84, 0xa0000
	s_addc_u32 s85, s85, 0
	global_load_dword v166, v250, s[28:29] offset:512
	global_load_dwordx4 v[220:223], v251, s[84:85]
	global_load_dwordx4 v[224:227], v251, s[84:85] offset:256
	s_add_u32 s84, s84, 0x20000
	s_addc_u32 s85, s85, 0
	global_load_dword v167, v250, s[28:29] offset:576
	global_load_dwordx4 v[228:231], v251, s[84:85]
	global_load_dwordx4 v[232:235], v251, s[84:85] offset:256
	s_add_u32 s84, s84, 0x20000
	s_addc_u32 s85, s85, 0
	global_load_dword v168, v250, s[28:29] offset:640
	global_load_dwordx4 v[236:239], v251, s[84:85]
	global_load_dwordx4 v[240:243], v251, s[84:85] offset:256
	s_waitcnt vmcnt(18)
	v_fmamk_f32 v178, v162, 0x39800000, v185
	v_rsq_f32_e32 v178, v178
	s_nop 0
	v_mul_f32_e32 v178, 0x41e1c71c, v178
	v_lshlrev_b32_e32 v170, 16, v188
	v_and_b32_e32 v171, 0xffff0000, v188
	v_lshlrev_b32_e32 v172, 16, v189
	v_and_b32_e32 v173, 0xffff0000, v189
	v_add_f32_e32 v126, v126, v170
	v_add_f32_e32 v127, v127, v171
	v_add_f32_e32 v128, v128, v172
	v_add_f32_e32 v129, v129, v173
	v_cvt_pk_bf16_f32 v244, v126, v127
	v_cvt_pk_bf16_f32 v245, v128, v129
	v_mul_f32_e32 v174, v178, v126
	v_mul_f32_e32 v175, v178, v127
	v_mul_f32_e32 v176, v178, v128
	v_mul_f32_e32 v177, v178, v129
	v_rndne_f32_e32 v174, v174
	v_rndne_f32_e32 v175, v175
	v_rndne_f32_e32 v176, v176
	v_rndne_f32_e32 v177, v177
	v_med3_f32 v174, v174, s50, v186
	v_med3_f32 v175, v175, s50, v186
	v_med3_f32 v176, v176, s50, v186
	v_med3_f32 v177, v177, s50, v186
	v_cvt_i32_f32_e32 v174, v174
	v_cvt_i32_f32_e32 v175, v175
	v_cvt_i32_f32_e32 v176, v176
	v_cvt_i32_f32_e32 v177, v177
	v_and_b32_e32 v174, 0xff, v174
	v_and_b32_e32 v175, 0xff, v175
	v_and_b32_e32 v176, 0xff, v176
	v_lshl_or_b32 v174, v175, 8, v174
	v_lshl_or_b32 v174, v176, 16, v174
	v_lshl_or_b32 v248, v177, 24, v174
	v_lshlrev_b32_e32 v170, 16, v190
	v_and_b32_e32 v171, 0xffff0000, v190
	v_lshlrev_b32_e32 v172, 16, v191
	v_and_b32_e32 v173, 0xffff0000, v191
	v_add_f32_e32 v122, v122, v170
	v_add_f32_e32 v123, v123, v171
	v_add_f32_e32 v124, v124, v172
	v_add_f32_e32 v125, v125, v173
	v_cvt_pk_bf16_f32 v246, v122, v123
	v_cvt_pk_bf16_f32 v247, v124, v125
	v_mul_f32_e32 v174, v178, v122
	v_mul_f32_e32 v175, v178, v123
	v_mul_f32_e32 v176, v178, v124
	v_mul_f32_e32 v177, v178, v125
	v_rndne_f32_e32 v174, v174
	v_rndne_f32_e32 v175, v175
	v_rndne_f32_e32 v176, v176
	v_rndne_f32_e32 v177, v177
	v_med3_f32 v174, v174, s50, v186
	v_med3_f32 v175, v175, s50, v186
	v_med3_f32 v176, v176, s50, v186
	v_med3_f32 v177, v177, s50, v186
	v_cvt_i32_f32_e32 v174, v174
	v_cvt_i32_f32_e32 v175, v175
	v_cvt_i32_f32_e32 v176, v176
	v_cvt_i32_f32_e32 v177, v177
	v_and_b32_e32 v174, 0xff, v174
	v_and_b32_e32 v175, 0xff, v175
	v_and_b32_e32 v176, 0xff, v176
	v_lshl_or_b32 v174, v175, 8, v174
	v_lshl_or_b32 v174, v176, 16, v174
	v_lshl_or_b32 v249, v177, 24, v174
	global_store_dwordx4 v251, v[244:247], s[86:87]
	global_store_dwordx2 v252, v[248:249], s[88:89]
	s_nop 0
	v_lshlrev_b32_e32 v170, 16, v192
	v_and_b32_e32 v171, 0xffff0000, v192
	v_lshlrev_b32_e32 v172, 16, v193
	v_and_b32_e32 v173, 0xffff0000, v193
	v_add_f32_e32 v118, v118, v170
	v_add_f32_e32 v119, v119, v171
	v_add_f32_e32 v120, v120, v172
	v_add_f32_e32 v121, v121, v173
	v_cvt_pk_bf16_f32 v244, v118, v119
	v_cvt_pk_bf16_f32 v245, v120, v121
	v_mul_f32_e32 v174, v178, v118
	v_mul_f32_e32 v175, v178, v119
	v_mul_f32_e32 v176, v178, v120
	v_mul_f32_e32 v177, v178, v121
	v_rndne_f32_e32 v174, v174
	v_rndne_f32_e32 v175, v175
	v_rndne_f32_e32 v176, v176
	v_rndne_f32_e32 v177, v177
	v_med3_f32 v174, v174, s50, v186
	v_med3_f32 v175, v175, s50, v186
	v_med3_f32 v176, v176, s50, v186
	v_med3_f32 v177, v177, s50, v186
	v_cvt_i32_f32_e32 v174, v174
	v_cvt_i32_f32_e32 v175, v175
	v_cvt_i32_f32_e32 v176, v176
	v_cvt_i32_f32_e32 v177, v177
	v_and_b32_e32 v174, 0xff, v174
	v_and_b32_e32 v175, 0xff, v175
	v_and_b32_e32 v176, 0xff, v176
	v_lshl_or_b32 v174, v175, 8, v174
	v_lshl_or_b32 v174, v176, 16, v174
	v_lshl_or_b32 v248, v177, 24, v174
	v_lshlrev_b32_e32 v170, 16, v194
	v_and_b32_e32 v171, 0xffff0000, v194
	v_lshlrev_b32_e32 v172, 16, v195
	v_and_b32_e32 v173, 0xffff0000, v195
	v_add_f32_e32 v114, v114, v170
	v_add_f32_e32 v115, v115, v171
	v_add_f32_e32 v116, v116, v172
	v_add_f32_e32 v117, v117, v173
	v_cvt_pk_bf16_f32 v246, v114, v115
	v_cvt_pk_bf16_f32 v247, v116, v117
	v_mul_f32_e32 v174, v178, v114
	v_mul_f32_e32 v175, v178, v115
	v_mul_f32_e32 v176, v178, v116
	v_mul_f32_e32 v177, v178, v117
	v_rndne_f32_e32 v174, v174
	v_rndne_f32_e32 v175, v175
	v_rndne_f32_e32 v176, v176
	v_rndne_f32_e32 v177, v177
	v_med3_f32 v174, v174, s50, v186
	v_med3_f32 v175, v175, s50, v186
	v_med3_f32 v176, v176, s50, v186
	v_med3_f32 v177, v177, s50, v186
	v_cvt_i32_f32_e32 v174, v174
	v_cvt_i32_f32_e32 v175, v175
	v_cvt_i32_f32_e32 v176, v176
	v_cvt_i32_f32_e32 v177, v177
	v_and_b32_e32 v174, 0xff, v174
	v_and_b32_e32 v175, 0xff, v175
	v_and_b32_e32 v176, 0xff, v176
	v_lshl_or_b32 v174, v175, 8, v174
	v_lshl_or_b32 v174, v176, 16, v174
	v_lshl_or_b32 v249, v177, 24, v174
	global_store_dwordx4 v251, v[244:247], s[86:87] offset:256
	global_store_dwordx2 v252, v[248:249], s[88:89] offset:128
	s_nop 0
	s_add_u32 s86, s86, 0x20000
	s_addc_u32 s87, s87, 0
	s_add_u32 s88, s88, 0x10000
	s_addc_u32 s89, s89, 0
	s_add_u32 s84, s84, 0x20000
	s_addc_u32 s85, s85, 0
	global_load_dword v162, v250, s[28:29] offset:704
	global_load_dwordx4 v[188:191], v251, s[84:85]
	global_load_dwordx4 v[192:195], v251, s[84:85] offset:256
	s_waitcnt vmcnt(22)
; __device__ __forceinline__ u32x4 pack8(const f32x4 a, const f32x4 b) { u32x4 w; w.x = cvt_pk_bf16(a[0], a[1]); w.y = cvt_pk_bf16(a[2], a[3]); w.z = cvt_pk_bf16(b[0], b[1]); w.w = cvt_pk_bf16(b[2], b[3]); return w; }
;     __device__ __forceinline__ void operator()(const f32x4 (&acc)[2][2][4][2], const pg8::Unit& u, int wr, int wc, int fr, int fq) const {
;     ...
;                 for (int bj = 0; bj < 2; ++bj) hr[m][bj] = *(const u32x4*)(HB + (size_t)(row0 + ai * 128 + m * 16) * DM + col0 + bj * 128); }
; #pragma unroll
;             for (int m = 0; m < 4; ++m) { const float iq = (127.f / QCLIP) * rsqrtf(q1v[m] * (1.f / DM) + EPS);
; #pragma unroll
;                 for (int bj = 0; bj < 2; ++bj) { float hv[8]; unpack8(hr[m][bj], hv); const size_t off = (size_t)(row0 + ai * 128 + m * 16) * DM + col0 + bj * 128;
;                     f32x4 h0 = acc[ai][bj][m][0], h1 = acc[ai][bj][m][1];
; #pragma unroll
;                     for (int e = 0; e < 4; ++e) { h0[e] += hv[e]; h1[e] += hv[4 + e]; }
;                     *(u32x4*)(HB + off) = pack8(h0, h1);
;                     f32x4 q0, q1;
; #pragma unroll
;                     for (int ee = 0; ee < 4; ++ee) { q0[ee] = fminf(fmaxf(rintf(h0[ee] * iq), -127.f), 127.f); q1[ee] = fminf(fmaxf(rintf(h1[ee] * iq), -127.f), 127.f); }
;                     *(u32x2*)(HQ + off) = pack8_i8(q0, q1); } }
;             asm volatile("" ::: "memory"); }
	v_fmamk_f32 v178, v163, 0x39800000, v185
	v_rsq_f32_e32 v178, v178
	s_nop 0
	v_mul_f32_e32 v178, 0x41e1c71c, v178
	v_lshlrev_b32_e32 v170, 16, v196
	v_and_b32_e32 v171, 0xffff0000, v196
	v_lshlrev_b32_e32 v172, 16, v197
	v_and_b32_e32 v173, 0xffff0000, v197
	v_add_f32_e32 v110, v110, v170
	v_add_f32_e32 v111, v111, v171
	v_add_f32_e32 v112, v112, v172
	v_add_f32_e32 v113, v113, v173
	v_cvt_pk_bf16_f32 v244, v110, v111
	v_cvt_pk_bf16_f32 v245, v112, v113
	v_mul_f32_e32 v174, v178, v110
	v_mul_f32_e32 v175, v178, v111
	v_mul_f32_e32 v176, v178, v112
	v_mul_f32_e32 v177, v178, v113
	v_rndne_f32_e32 v174, v174
	v_rndne_f32_e32 v175, v175
	v_rndne_f32_e32 v176, v176
	v_rndne_f32_e32 v177, v177
	v_med3_f32 v174, v174, s50, v186
	v_med3_f32 v175, v175, s50, v186
	v_med3_f32 v176, v176, s50, v186
	v_med3_f32 v177, v177, s50, v186
	v_cvt_i32_f32_e32 v174, v174
	v_cvt_i32_f32_e32 v175, v175
	v_cvt_i32_f32_e32 v176, v176
	v_cvt_i32_f32_e32 v177, v177
	v_and_b32_e32 v174, 0xff, v174
	v_and_b32_e32 v175, 0xff, v175
	v_and_b32_e32 v176, 0xff, v176
	v_lshl_or_b32 v174, v175, 8, v174
	v_lshl_or_b32 v174, v176, 16, v174
	v_lshl_or_b32 v248, v177, 24, v174
	v_lshlrev_b32_e32 v170, 16, v198
	v_and_b32_e32 v171, 0xffff0000, v198
	v_lshlrev_b32_e32 v172, 16, v199
	v_and_b32_e32 v173, 0xffff0000, v199
	v_add_f32_e32 v106, v106, v170
	v_add_f32_e32 v107, v107, v171
	v_add_f32_e32 v108, v108, v172
	v_add_f32_e32 v109, v109, v173
	v_cvt_pk_bf16_f32 v246, v106, v107
	v_cvt_pk_bf16_f32 v247, v108, v109
	v_mul_f32_e32 v174, v178, v106
	v_mul_f32_e32 v175, v178, v107
	v_mul_f32_e32 v176, v178, v108
	v_mul_f32_e32 v177, v178, v109
	v_rndne_f32_e32 v174, v174
	v_rndne_f32_e32 v175, v175
	v_rndne_f32_e32 v176, v176
	v_rndne_f32_e32 v177, v177
	v_med3_f32 v174, v174, s50, v186
	v_med3_f32 v175, v175, s50, v186
	v_med3_f32 v176, v176, s50, v186
	v_med3_f32 v177, v177, s50, v186
	v_cvt_i32_f32_e32 v174, v174
	v_cvt_i32_f32_e32 v175, v175
	v_cvt_i32_f32_e32 v176, v176
	v_cvt_i32_f32_e32 v177, v177
	v_and_b32_e32 v174, 0xff, v174
	v_and_b32_e32 v175, 0xff, v175
	v_and_b32_e32 v176, 0xff, v176
	v_lshl_or_b32 v174, v175, 8, v174
	v_lshl_or_b32 v174, v176, 16, v174
	v_lshl_or_b32 v249, v177, 24, v174
	global_store_dwordx4 v251, v[244:247], s[86:87]
	global_store_dwordx2 v252, v[248:249], s[88:89]
	s_nop 0
	v_lshlrev_b32_e32 v170, 16, v200
	v_and_b32_e32 v171, 0xffff0000, v200
	v_lshlrev_b32_e32 v172, 16, v201
	v_and_b32_e32 v173, 0xffff0000, v201
	v_add_f32_e32 v102, v102, v170
	v_add_f32_e32 v103, v103, v171
	v_add_f32_e32 v104, v104, v172
	v_add_f32_e32 v105, v105, v173
	v_cvt_pk_bf16_f32 v244, v102, v103
	v_cvt_pk_bf16_f32 v245, v104, v105
	v_mul_f32_e32 v174, v178, v102
	v_mul_f32_e32 v175, v178, v103
	v_mul_f32_e32 v176, v178, v104
	v_mul_f32_e32 v177, v178, v105
	v_rndne_f32_e32 v174, v174
	v_rndne_f32_e32 v175, v175
	v_rndne_f32_e32 v176, v176
	v_rndne_f32_e32 v177, v177
	v_med3_f32 v174, v174, s50, v186
	v_med3_f32 v175, v175, s50, v186
	v_med3_f32 v176, v176, s50, v186
	v_med3_f32 v177, v177, s50, v186
	v_cvt_i32_f32_e32 v174, v174
	v_cvt_i32_f32_e32 v175, v175
	v_cvt_i32_f32_e32 v176, v176
	v_cvt_i32_f32_e32 v177, v177
	v_and_b32_e32 v174, 0xff, v174
	v_and_b32_e32 v175, 0xff, v175
	v_and_b32_e32 v176, 0xff, v176
	v_lshl_or_b32 v174, v175, 8, v174
	v_lshl_or_b32 v174, v176, 16, v174
	v_lshl_or_b32 v248, v177, 24, v174
	v_lshlrev_b32_e32 v170, 16, v202
	v_and_b32_e32 v171, 0xffff0000, v202
	v_lshlrev_b32_e32 v172, 16, v203
	v_and_b32_e32 v173, 0xffff0000, v203
	v_add_f32_e32 v98, v98, v170
	v_add_f32_e32 v99, v99, v171
	v_add_f32_e32 v100, v100, v172
	v_add_f32_e32 v101, v101, v173
	v_cvt_pk_bf16_f32 v246, v98, v99
	v_cvt_pk_bf16_f32 v247, v100, v101
	v_mul_f32_e32 v174, v178, v98
	v_mul_f32_e32 v175, v178, v99
	v_mul_f32_e32 v176, v178, v100
	v_mul_f32_e32 v177, v178, v101
	v_rndne_f32_e32 v174, v174
	v_rndne_f32_e32 v175, v175
	v_rndne_f32_e32 v176, v176
	v_rndne_f32_e32 v177, v177
	v_med3_f32 v174, v174, s50, v186
	v_med3_f32 v175, v175, s50, v186
	v_med3_f32 v176, v176, s50, v186
	v_med3_f32 v177, v177, s50, v186
	v_cvt_i32_f32_e32 v174, v174
	v_cvt_i32_f32_e32 v175, v175
	v_cvt_i32_f32_e32 v176, v176
	v_cvt_i32_f32_e32 v177, v177
	v_and_b32_e32 v174, 0xff, v174
	v_and_b32_e32 v175, 0xff, v175
	v_and_b32_e32 v176, 0xff, v176
	v_lshl_or_b32 v174, v175, 8, v174
	v_lshl_or_b32 v174, v176, 16, v174
	v_lshl_or_b32 v249, v177, 24, v174
	global_store_dwordx4 v251, v[244:247], s[86:87] offset:256
	global_store_dwordx2 v252, v[248:249], s[88:89] offset:128
	s_nop 0
	s_add_u32 s86, s86, 0x20000
	s_addc_u32 s87, s87, 0
	s_add_u32 s88, s88, 0x10000
	s_addc_u32 s89, s89, 0
	s_waitcnt vmcnt(23)
; __device__ __forceinline__ u32x4 pack8(const f32x4 a, const f32x4 b) { u32x4 w; w.x = cvt_pk_bf16(a[0], a[1]); w.y = cvt_pk_bf16(a[2], a[3]); w.z = cvt_pk_bf16(b[0], b[1]); w.w = cvt_pk_bf16(b[2], b[3]); return w; }
;     __device__ __forceinline__ void operator()(const f32x4 (&acc)[2][2][4][2], const pg8::Unit& u, int wr, int wc, int fr, int fq) const {
;     ...
;                 for (int bj = 0; bj < 2; ++bj) hr[m][bj] = *(const u32x4*)(HB + (size_t)(row0 + ai * 128 + m * 16) * DM + col0 + bj * 128); }
; #pragma unroll
;             for (int m = 0; m < 4; ++m) { const float iq = (127.f / QCLIP) * rsqrtf(q1v[m] * (1.f / DM) + EPS);
; #pragma unroll
;                 for (int bj = 0; bj < 2; ++bj) { float hv[8]; unpack8(hr[m][bj], hv); const size_t off = (size_t)(row0 + ai * 128 + m * 16) * DM + col0 + bj * 128;
;                     f32x4 h0 = acc[ai][bj][m][0], h1 = acc[ai][bj][m][1];
; #pragma unroll
;                     for (int e = 0; e < 4; ++e) { h0[e] += hv[e]; h1[e] += hv[4 + e]; }
;                     *(u32x4*)(HB + off) = pack8(h0, h1);
;                     f32x4 q0, q1;
; #pragma unroll
;                     for (int ee = 0; ee < 4; ++ee) { q0[ee] = fminf(fmaxf(rintf(h0[ee] * iq), -127.f), 127.f); q1[ee] = fminf(fmaxf(rintf(h1[ee] * iq), -127.f), 127.f); }
;                     *(u32x2*)(HQ + off) = pack8_i8(q0, q1); } }
;             asm volatile("" ::: "memory"); }
	v_fmamk_f32 v178, v164, 0x39800000, v185
	v_rsq_f32_e32 v178, v178
	s_nop 0
	v_mul_f32_e32 v178, 0x41e1c71c, v178
	v_lshlrev_b32_e32 v170, 16, v204
	v_and_b32_e32 v171, 0xffff0000, v204
	v_lshlrev_b32_e32 v172, 16, v205
	v_and_b32_e32 v173, 0xffff0000, v205
	v_add_f32_e32 v94, v94, v170
	v_add_f32_e32 v95, v95, v171
	v_add_f32_e32 v96, v96, v172
	v_add_f32_e32 v97, v97, v173
	v_cvt_pk_bf16_f32 v244, v94, v95
	v_cvt_pk_bf16_f32 v245, v96, v97
	v_mul_f32_e32 v174, v178, v94
	v_mul_f32_e32 v175, v178, v95
	v_mul_f32_e32 v176, v178, v96
	v_mul_f32_e32 v177, v178, v97
	v_rndne_f32_e32 v174, v174
	v_rndne_f32_e32 v175, v175
	v_rndne_f32_e32 v176, v176
	v_rndne_f32_e32 v177, v177
	v_med3_f32 v174, v174, s50, v186
	v_med3_f32 v175, v175, s50, v186
	v_med3_f32 v176, v176, s50, v186
	v_med3_f32 v177, v177, s50, v186
	v_cvt_i32_f32_e32 v174, v174
	v_cvt_i32_f32_e32 v175, v175
	v_cvt_i32_f32_e32 v176, v176
	v_cvt_i32_f32_e32 v177, v177
	v_and_b32_e32 v174, 0xff, v174
	v_and_b32_e32 v175, 0xff, v175
	v_and_b32_e32 v176, 0xff, v176
	v_lshl_or_b32 v174, v175, 8, v174
	v_lshl_or_b32 v174, v176, 16, v174
	v_lshl_or_b32 v248, v177, 24, v174
	v_lshlrev_b32_e32 v170, 16, v206
	v_and_b32_e32 v171, 0xffff0000, v206
	v_lshlrev_b32_e32 v172, 16, v207
	v_and_b32_e32 v173, 0xffff0000, v207
	v_add_f32_e32 v90, v90, v170
	v_add_f32_e32 v91, v91, v171
	v_add_f32_e32 v92, v92, v172
	v_add_f32_e32 v93, v93, v173
	v_cvt_pk_bf16_f32 v246, v90, v91
	v_cvt_pk_bf16_f32 v247, v92, v93
	v_mul_f32_e32 v174, v178, v90
	v_mul_f32_e32 v175, v178, v91
	v_mul_f32_e32 v176, v178, v92
	v_mul_f32_e32 v177, v178, v93
	v_rndne_f32_e32 v174, v174
	v_rndne_f32_e32 v175, v175
	v_rndne_f32_e32 v176, v176
	v_rndne_f32_e32 v177, v177
	v_med3_f32 v174, v174, s50, v186
	v_med3_f32 v175, v175, s50, v186
	v_med3_f32 v176, v176, s50, v186
	v_med3_f32 v177, v177, s50, v186
	v_cvt_i32_f32_e32 v174, v174
	v_cvt_i32_f32_e32 v175, v175
	v_cvt_i32_f32_e32 v176, v176
	v_cvt_i32_f32_e32 v177, v177
	v_and_b32_e32 v174, 0xff, v174
	v_and_b32_e32 v175, 0xff, v175
	v_and_b32_e32 v176, 0xff, v176
	v_lshl_or_b32 v174, v175, 8, v174
	v_lshl_or_b32 v174, v176, 16, v174
	v_lshl_or_b32 v249, v177, 24, v174
	global_store_dwordx4 v251, v[244:247], s[86:87]
	global_store_dwordx2 v252, v[248:249], s[88:89]
	s_nop 0
	v_lshlrev_b32_e32 v170, 16, v208
	v_and_b32_e32 v171, 0xffff0000, v208
	v_lshlrev_b32_e32 v172, 16, v209
	v_and_b32_e32 v173, 0xffff0000, v209
	v_add_f32_e32 v86, v86, v170
	v_add_f32_e32 v87, v87, v171
	v_add_f32_e32 v88, v88, v172
	v_add_f32_e32 v89, v89, v173
	v_cvt_pk_bf16_f32 v244, v86, v87
	v_cvt_pk_bf16_f32 v245, v88, v89
	v_mul_f32_e32 v174, v178, v86
	v_mul_f32_e32 v175, v178, v87
	v_mul_f32_e32 v176, v178, v88
	v_mul_f32_e32 v177, v178, v89
	v_rndne_f32_e32 v174, v174
	v_rndne_f32_e32 v175, v175
	v_rndne_f32_e32 v176, v176
	v_rndne_f32_e32 v177, v177
	v_med3_f32 v174, v174, s50, v186
	v_med3_f32 v175, v175, s50, v186
	v_med3_f32 v176, v176, s50, v186
	v_med3_f32 v177, v177, s50, v186
	v_cvt_i32_f32_e32 v174, v174
	v_cvt_i32_f32_e32 v175, v175
	v_cvt_i32_f32_e32 v176, v176
	v_cvt_i32_f32_e32 v177, v177
	v_and_b32_e32 v174, 0xff, v174
	v_and_b32_e32 v175, 0xff, v175
	v_and_b32_e32 v176, 0xff, v176
	v_lshl_or_b32 v174, v175, 8, v174
	v_lshl_or_b32 v174, v176, 16, v174
	v_lshl_or_b32 v248, v177, 24, v174
	v_lshlrev_b32_e32 v170, 16, v210
	v_and_b32_e32 v171, 0xffff0000, v210
	v_lshlrev_b32_e32 v172, 16, v211
	v_and_b32_e32 v173, 0xffff0000, v211
	v_add_f32_e32 v82, v82, v170
	v_add_f32_e32 v83, v83, v171
	v_add_f32_e32 v84, v84, v172
	v_add_f32_e32 v85, v85, v173
	v_cvt_pk_bf16_f32 v246, v82, v83
	v_cvt_pk_bf16_f32 v247, v84, v85
	v_mul_f32_e32 v174, v178, v82
	v_mul_f32_e32 v175, v178, v83
	v_mul_f32_e32 v176, v178, v84
	v_mul_f32_e32 v177, v178, v85
	v_rndne_f32_e32 v174, v174
	v_rndne_f32_e32 v175, v175
	v_rndne_f32_e32 v176, v176
	v_rndne_f32_e32 v177, v177
	v_med3_f32 v174, v174, s50, v186
	v_med3_f32 v175, v175, s50, v186
	v_med3_f32 v176, v176, s50, v186
	v_med3_f32 v177, v177, s50, v186
	v_cvt_i32_f32_e32 v174, v174
	v_cvt_i32_f32_e32 v175, v175
	v_cvt_i32_f32_e32 v176, v176
	v_cvt_i32_f32_e32 v177, v177
	v_and_b32_e32 v174, 0xff, v174
	v_and_b32_e32 v175, 0xff, v175
	v_and_b32_e32 v176, 0xff, v176
	v_lshl_or_b32 v174, v175, 8, v174
	v_lshl_or_b32 v174, v176, 16, v174
	v_lshl_or_b32 v249, v177, 24, v174
	global_store_dwordx4 v251, v[244:247], s[86:87] offset:256
	global_store_dwordx2 v252, v[248:249], s[88:89] offset:128
	s_nop 0
	s_add_u32 s86, s86, 0x20000
	s_addc_u32 s87, s87, 0
	s_add_u32 s88, s88, 0x10000
	s_addc_u32 s89, s89, 0
	s_waitcnt vmcnt(24)
; __device__ __forceinline__ u32x4 pack8(const f32x4 a, const f32x4 b) { u32x4 w; w.x = cvt_pk_bf16(a[0], a[1]); w.y = cvt_pk_bf16(a[2], a[3]); w.z = cvt_pk_bf16(b[0], b[1]); w.w = cvt_pk_bf16(b[2], b[3]); return w; }
;     __device__ __forceinline__ void operator()(const f32x4 (&acc)[2][2][4][2], const pg8::Unit& u, int wr, int wc, int fr, int fq) const {
;     ...
;                 for (int bj = 0; bj < 2; ++bj) hr[m][bj] = *(const u32x4*)(HB + (size_t)(row0 + ai * 128 + m * 16) * DM + col0 + bj * 128); }
; #pragma unroll
;             for (int m = 0; m < 4; ++m) { const float iq = (127.f / QCLIP) * rsqrtf(q1v[m] * (1.f / DM) + EPS);
; #pragma unroll
;                 for (int bj = 0; bj < 2; ++bj) { float hv[8]; unpack8(hr[m][bj], hv); const size_t off = (size_t)(row0 + ai * 128 + m * 16) * DM + col0 + bj * 128;
;                     f32x4 h0 = acc[ai][bj][m][0], h1 = acc[ai][bj][m][1];
; #pragma unroll
;                     for (int e = 0; e < 4; ++e) { h0[e] += hv[e]; h1[e] += hv[4 + e]; }
;                     *(u32x4*)(HB + off) = pack8(h0, h1);
;                     f32x4 q0, q1;
; #pragma unroll
;                     for (int ee = 0; ee < 4; ++ee) { q0[ee] = fminf(fmaxf(rintf(h0[ee] * iq), -127.f), 127.f); q1[ee] = fminf(fmaxf(rintf(h1[ee] * iq), -127.f), 127.f); }
;                     *(u32x2*)(HQ + off) = pack8_i8(q0, q1); } }
;             asm volatile("" ::: "memory"); }
	v_fmamk_f32 v178, v165, 0x39800000, v185
	v_rsq_f32_e32 v178, v178
	s_nop 0
	v_mul_f32_e32 v178, 0x41e1c71c, v178
	v_lshlrev_b32_e32 v170, 16, v212
	v_and_b32_e32 v171, 0xffff0000, v212
	v_lshlrev_b32_e32 v172, 16, v213
	v_and_b32_e32 v173, 0xffff0000, v213
	v_add_f32_e32 v78, v78, v170
	v_add_f32_e32 v79, v79, v171
	v_add_f32_e32 v80, v80, v172
	v_add_f32_e32 v81, v81, v173
	v_cvt_pk_bf16_f32 v244, v78, v79
	v_cvt_pk_bf16_f32 v245, v80, v81
	v_mul_f32_e32 v174, v178, v78
	v_mul_f32_e32 v175, v178, v79
	v_mul_f32_e32 v176, v178, v80
	v_mul_f32_e32 v177, v178, v81
	v_rndne_f32_e32 v174, v174
	v_rndne_f32_e32 v175, v175
	v_rndne_f32_e32 v176, v176
	v_rndne_f32_e32 v177, v177
	v_med3_f32 v174, v174, s50, v186
	v_med3_f32 v175, v175, s50, v186
	v_med3_f32 v176, v176, s50, v186
	v_med3_f32 v177, v177, s50, v186
	v_cvt_i32_f32_e32 v174, v174
	v_cvt_i32_f32_e32 v175, v175
	v_cvt_i32_f32_e32 v176, v176
	v_cvt_i32_f32_e32 v177, v177
	v_and_b32_e32 v174, 0xff, v174
	v_and_b32_e32 v175, 0xff, v175
	v_and_b32_e32 v176, 0xff, v176
	v_lshl_or_b32 v174, v175, 8, v174
	v_lshl_or_b32 v174, v176, 16, v174
	v_lshl_or_b32 v248, v177, 24, v174
	v_lshlrev_b32_e32 v170, 16, v214
	v_and_b32_e32 v171, 0xffff0000, v214
	v_lshlrev_b32_e32 v172, 16, v215
	v_and_b32_e32 v173, 0xffff0000, v215
	v_add_f32_e32 v74, v74, v170
	v_add_f32_e32 v75, v75, v171
	v_add_f32_e32 v76, v76, v172
	v_add_f32_e32 v77, v77, v173
	v_cvt_pk_bf16_f32 v246, v74, v75
	v_cvt_pk_bf16_f32 v247, v76, v77
	v_mul_f32_e32 v174, v178, v74
	v_mul_f32_e32 v175, v178, v75
	v_mul_f32_e32 v176, v178, v76
	v_mul_f32_e32 v177, v178, v77
	v_rndne_f32_e32 v174, v174
	v_rndne_f32_e32 v175, v175
	v_rndne_f32_e32 v176, v176
	v_rndne_f32_e32 v177, v177
	v_med3_f32 v174, v174, s50, v186
	v_med3_f32 v175, v175, s50, v186
	v_med3_f32 v176, v176, s50, v186
	v_med3_f32 v177, v177, s50, v186
	v_cvt_i32_f32_e32 v174, v174
	v_cvt_i32_f32_e32 v175, v175
	v_cvt_i32_f32_e32 v176, v176
	v_cvt_i32_f32_e32 v177, v177
	v_and_b32_e32 v174, 0xff, v174
	v_and_b32_e32 v175, 0xff, v175
	v_and_b32_e32 v176, 0xff, v176
	v_lshl_or_b32 v174, v175, 8, v174
	v_lshl_or_b32 v174, v176, 16, v174
	v_lshl_or_b32 v249, v177, 24, v174
	global_store_dwordx4 v251, v[244:247], s[86:87]
	global_store_dwordx2 v252, v[248:249], s[88:89]
	s_nop 0
	v_lshlrev_b32_e32 v170, 16, v216
	v_and_b32_e32 v171, 0xffff0000, v216
	v_lshlrev_b32_e32 v172, 16, v217
	v_and_b32_e32 v173, 0xffff0000, v217
	v_add_f32_e32 v70, v70, v170
	v_add_f32_e32 v71, v71, v171
	v_add_f32_e32 v72, v72, v172
	v_add_f32_e32 v73, v73, v173
	v_cvt_pk_bf16_f32 v244, v70, v71
	v_cvt_pk_bf16_f32 v245, v72, v73
	v_mul_f32_e32 v174, v178, v70
	v_mul_f32_e32 v175, v178, v71
	v_mul_f32_e32 v176, v178, v72
	v_mul_f32_e32 v177, v178, v73
	v_rndne_f32_e32 v174, v174
	v_rndne_f32_e32 v175, v175
	v_rndne_f32_e32 v176, v176
	v_rndne_f32_e32 v177, v177
	v_med3_f32 v174, v174, s50, v186
	v_med3_f32 v175, v175, s50, v186
	v_med3_f32 v176, v176, s50, v186
	v_med3_f32 v177, v177, s50, v186
	v_cvt_i32_f32_e32 v174, v174
	v_cvt_i32_f32_e32 v175, v175
	v_cvt_i32_f32_e32 v176, v176
	v_cvt_i32_f32_e32 v177, v177
	v_and_b32_e32 v174, 0xff, v174
	v_and_b32_e32 v175, 0xff, v175
	v_and_b32_e32 v176, 0xff, v176
	v_lshl_or_b32 v174, v175, 8, v174
	v_lshl_or_b32 v174, v176, 16, v174
	v_lshl_or_b32 v248, v177, 24, v174
	v_lshlrev_b32_e32 v170, 16, v218
	v_and_b32_e32 v171, 0xffff0000, v218
	v_lshlrev_b32_e32 v172, 16, v219
	v_and_b32_e32 v173, 0xffff0000, v219
	v_add_f32_e32 v66, v66, v170
	v_add_f32_e32 v67, v67, v171
	v_add_f32_e32 v68, v68, v172
	v_add_f32_e32 v69, v69, v173
	v_cvt_pk_bf16_f32 v246, v66, v67
	v_cvt_pk_bf16_f32 v247, v68, v69
	v_mul_f32_e32 v174, v178, v66
	v_mul_f32_e32 v175, v178, v67
	v_mul_f32_e32 v176, v178, v68
	v_mul_f32_e32 v177, v178, v69
	v_rndne_f32_e32 v174, v174
	v_rndne_f32_e32 v175, v175
	v_rndne_f32_e32 v176, v176
	v_rndne_f32_e32 v177, v177
	v_med3_f32 v174, v174, s50, v186
	v_med3_f32 v175, v175, s50, v186
	v_med3_f32 v176, v176, s50, v186
	v_med3_f32 v177, v177, s50, v186
	v_cvt_i32_f32_e32 v174, v174
	v_cvt_i32_f32_e32 v175, v175
	v_cvt_i32_f32_e32 v176, v176
	v_cvt_i32_f32_e32 v177, v177
	v_and_b32_e32 v174, 0xff, v174
	v_and_b32_e32 v175, 0xff, v175
	v_and_b32_e32 v176, 0xff, v176
	v_lshl_or_b32 v174, v175, 8, v174
	v_lshl_or_b32 v174, v176, 16, v174
	v_lshl_or_b32 v249, v177, 24, v174
	global_store_dwordx4 v251, v[244:247], s[86:87] offset:256
	global_store_dwordx2 v252, v[248:249], s[88:89] offset:128
	s_nop 0
	s_add_u32 s86, s86, 0xa0000
	s_addc_u32 s87, s87, 0
	s_add_u32 s88, s88, 0x50000
	s_addc_u32 s89, s89, 0
	s_waitcnt vmcnt(25)
; __device__ __forceinline__ u32x4 pack8(const f32x4 a, const f32x4 b) { u32x4 w; w.x = cvt_pk_bf16(a[0], a[1]); w.y = cvt_pk_bf16(a[2], a[3]); w.z = cvt_pk_bf16(b[0], b[1]); w.w = cvt_pk_bf16(b[2], b[3]); return w; }
;     __device__ __forceinline__ void operator()(const f32x4 (&acc)[2][2][4][2], const pg8::Unit& u, int wr, int wc, int fr, int fq) const {
;     ...
;                 for (int bj = 0; bj < 2; ++bj) hr[m][bj] = *(const u32x4*)(HB + (size_t)(row0 + ai * 128 + m * 16) * DM + col0 + bj * 128); }
; #pragma unroll
;             for (int m = 0; m < 4; ++m) { const float iq = (127.f / QCLIP) * rsqrtf(q1v[m] * (1.f / DM) + EPS);
; #pragma unroll
;                 for (int bj = 0; bj < 2; ++bj) { float hv[8]; unpack8(hr[m][bj], hv); const size_t off = (size_t)(row0 + ai * 128 + m * 16) * DM + col0 + bj * 128;
;                     f32x4 h0 = acc[ai][bj][m][0], h1 = acc[ai][bj][m][1];
; #pragma unroll
;                     for (int e = 0; e < 4; ++e) { h0[e] += hv[e]; h1[e] += hv[4 + e]; }
;                     *(u32x4*)(HB + off) = pack8(h0, h1);
;                     f32x4 q0, q1;
; #pragma unroll
;                     for (int ee = 0; ee < 4; ++ee) { q0[ee] = fminf(fmaxf(rintf(h0[ee] * iq), -127.f), 127.f); q1[ee] = fminf(fmaxf(rintf(h1[ee] * iq), -127.f), 127.f); }
;                     *(u32x2*)(HQ + off) = pack8_i8(q0, q1); } }
;             asm volatile("" ::: "memory"); }
	v_fmamk_f32 v178, v166, 0x39800000, v185
	v_rsq_f32_e32 v178, v178
	s_nop 0
	v_mul_f32_e32 v178, 0x41e1c71c, v178
	v_lshlrev_b32_e32 v170, 16, v220
	v_and_b32_e32 v171, 0xffff0000, v220
	v_lshlrev_b32_e32 v172, 16, v221
	v_and_b32_e32 v173, 0xffff0000, v221
	v_add_f32_e32 v62, v62, v170
	v_add_f32_e32 v63, v63, v171
	v_add_f32_e32 v64, v64, v172
	v_add_f32_e32 v65, v65, v173
	v_cvt_pk_bf16_f32 v244, v62, v63
	v_cvt_pk_bf16_f32 v245, v64, v65
	v_mul_f32_e32 v174, v178, v62
	v_mul_f32_e32 v175, v178, v63
	v_mul_f32_e32 v176, v178, v64
	v_mul_f32_e32 v177, v178, v65
	v_rndne_f32_e32 v174, v174
	v_rndne_f32_e32 v175, v175
	v_rndne_f32_e32 v176, v176
	v_rndne_f32_e32 v177, v177
	v_med3_f32 v174, v174, s50, v186
	v_med3_f32 v175, v175, s50, v186
	v_med3_f32 v176, v176, s50, v186
	v_med3_f32 v177, v177, s50, v186
	v_cvt_i32_f32_e32 v174, v174
	v_cvt_i32_f32_e32 v175, v175
	v_cvt_i32_f32_e32 v176, v176
	v_cvt_i32_f32_e32 v177, v177
	v_and_b32_e32 v174, 0xff, v174
	v_and_b32_e32 v175, 0xff, v175
	v_and_b32_e32 v176, 0xff, v176
	v_lshl_or_b32 v174, v175, 8, v174
	v_lshl_or_b32 v174, v176, 16, v174
	v_lshl_or_b32 v248, v177, 24, v174
	v_lshlrev_b32_e32 v170, 16, v222
	v_and_b32_e32 v171, 0xffff0000, v222
	v_lshlrev_b32_e32 v172, 16, v223
	v_and_b32_e32 v173, 0xffff0000, v223
	v_add_f32_e32 v58, v58, v170
	v_add_f32_e32 v59, v59, v171
	v_add_f32_e32 v60, v60, v172
	v_add_f32_e32 v61, v61, v173
	v_cvt_pk_bf16_f32 v246, v58, v59
	v_cvt_pk_bf16_f32 v247, v60, v61
	v_mul_f32_e32 v174, v178, v58
	v_mul_f32_e32 v175, v178, v59
	v_mul_f32_e32 v176, v178, v60
	v_mul_f32_e32 v177, v178, v61
	v_rndne_f32_e32 v174, v174
	v_rndne_f32_e32 v175, v175
	v_rndne_f32_e32 v176, v176
	v_rndne_f32_e32 v177, v177
	v_med3_f32 v174, v174, s50, v186
	v_med3_f32 v175, v175, s50, v186
	v_med3_f32 v176, v176, s50, v186
	v_med3_f32 v177, v177, s50, v186
	v_cvt_i32_f32_e32 v174, v174
	v_cvt_i32_f32_e32 v175, v175
	v_cvt_i32_f32_e32 v176, v176
	v_cvt_i32_f32_e32 v177, v177
	v_and_b32_e32 v174, 0xff, v174
	v_and_b32_e32 v175, 0xff, v175
	v_and_b32_e32 v176, 0xff, v176
	v_lshl_or_b32 v174, v175, 8, v174
	v_lshl_or_b32 v174, v176, 16, v174
	v_lshl_or_b32 v249, v177, 24, v174
	global_store_dwordx4 v251, v[244:247], s[86:87]
	global_store_dwordx2 v252, v[248:249], s[88:89]
	s_nop 0
	v_lshlrev_b32_e32 v170, 16, v224
	v_and_b32_e32 v171, 0xffff0000, v224
	v_lshlrev_b32_e32 v172, 16, v225
	v_and_b32_e32 v173, 0xffff0000, v225
	v_add_f32_e32 v54, v54, v170
	v_add_f32_e32 v55, v55, v171
	v_add_f32_e32 v56, v56, v172
	v_add_f32_e32 v57, v57, v173
	v_cvt_pk_bf16_f32 v244, v54, v55
	v_cvt_pk_bf16_f32 v245, v56, v57
	v_mul_f32_e32 v174, v178, v54
	v_mul_f32_e32 v175, v178, v55
	v_mul_f32_e32 v176, v178, v56
	v_mul_f32_e32 v177, v178, v57
	v_rndne_f32_e32 v174, v174
	v_rndne_f32_e32 v175, v175
	v_rndne_f32_e32 v176, v176
	v_rndne_f32_e32 v177, v177
	v_med3_f32 v174, v174, s50, v186
	v_med3_f32 v175, v175, s50, v186
	v_med3_f32 v176, v176, s50, v186
	v_med3_f32 v177, v177, s50, v186
	v_cvt_i32_f32_e32 v174, v174
	v_cvt_i32_f32_e32 v175, v175
	v_cvt_i32_f32_e32 v176, v176
	v_cvt_i32_f32_e32 v177, v177
	v_and_b32_e32 v174, 0xff, v174
	v_and_b32_e32 v175, 0xff, v175
	v_and_b32_e32 v176, 0xff, v176
	v_lshl_or_b32 v174, v175, 8, v174
	v_lshl_or_b32 v174, v176, 16, v174
	v_lshl_or_b32 v248, v177, 24, v174
	v_lshlrev_b32_e32 v170, 16, v226
	v_and_b32_e32 v171, 0xffff0000, v226
	v_lshlrev_b32_e32 v172, 16, v227
	v_and_b32_e32 v173, 0xffff0000, v227
	v_add_f32_e32 v50, v50, v170
	v_add_f32_e32 v51, v51, v171
	v_add_f32_e32 v52, v52, v172
	v_add_f32_e32 v53, v53, v173
	v_cvt_pk_bf16_f32 v246, v50, v51
	v_cvt_pk_bf16_f32 v247, v52, v53
	v_mul_f32_e32 v174, v178, v50
	v_mul_f32_e32 v175, v178, v51
	v_mul_f32_e32 v176, v178, v52
	v_mul_f32_e32 v177, v178, v53
	v_rndne_f32_e32 v174, v174
	v_rndne_f32_e32 v175, v175
	v_rndne_f32_e32 v176, v176
	v_rndne_f32_e32 v177, v177
	v_med3_f32 v174, v174, s50, v186
	v_med3_f32 v175, v175, s50, v186
	v_med3_f32 v176, v176, s50, v186
	v_med3_f32 v177, v177, s50, v186
	v_cvt_i32_f32_e32 v174, v174
	v_cvt_i32_f32_e32 v175, v175
	v_cvt_i32_f32_e32 v176, v176
	v_cvt_i32_f32_e32 v177, v177
	v_and_b32_e32 v174, 0xff, v174
	v_and_b32_e32 v175, 0xff, v175
	v_and_b32_e32 v176, 0xff, v176
	v_lshl_or_b32 v174, v175, 8, v174
	v_lshl_or_b32 v174, v176, 16, v174
	v_lshl_or_b32 v249, v177, 24, v174
	global_store_dwordx4 v251, v[244:247], s[86:87] offset:256
	global_store_dwordx2 v252, v[248:249], s[88:89] offset:128
	s_nop 0
	s_add_u32 s86, s86, 0x20000
	s_addc_u32 s87, s87, 0
	s_add_u32 s88, s88, 0x10000
	s_addc_u32 s89, s89, 0
	s_waitcnt vmcnt(26)
; __device__ __forceinline__ u32x4 pack8(const f32x4 a, const f32x4 b) { u32x4 w; w.x = cvt_pk_bf16(a[0], a[1]); w.y = cvt_pk_bf16(a[2], a[3]); w.z = cvt_pk_bf16(b[0], b[1]); w.w = cvt_pk_bf16(b[2], b[3]); return w; }
;     __device__ __forceinline__ void operator()(const f32x4 (&acc)[2][2][4][2], const pg8::Unit& u, int wr, int wc, int fr, int fq) const {
;     ...
;                 for (int bj = 0; bj < 2; ++bj) hr[m][bj] = *(const u32x4*)(HB + (size_t)(row0 + ai * 128 + m * 16) * DM + col0 + bj * 128); }
; #pragma unroll
;             for (int m = 0; m < 4; ++m) { const float iq = (127.f / QCLIP) * rsqrtf(q1v[m] * (1.f / DM) + EPS);
; #pragma unroll
;                 for (int bj = 0; bj < 2; ++bj) { float hv[8]; unpack8(hr[m][bj], hv); const size_t off = (size_t)(row0 + ai * 128 + m * 16) * DM + col0 + bj * 128;
;                     f32x4 h0 = acc[ai][bj][m][0], h1 = acc[ai][bj][m][1];
; #pragma unroll
;                     for (int e = 0; e < 4; ++e) { h0[e] += hv[e]; h1[e] += hv[4 + e]; }
;                     *(u32x4*)(HB + off) = pack8(h0, h1);
;                     f32x4 q0, q1;
; #pragma unroll
;                     for (int ee = 0; ee < 4; ++ee) { q0[ee] = fminf(fmaxf(rintf(h0[ee] * iq), -127.f), 127.f); q1[ee] = fminf(fmaxf(rintf(h1[ee] * iq), -127.f), 127.f); }
;                     *(u32x2*)(HQ + off) = pack8_i8(q0, q1); } }
;             asm volatile("" ::: "memory"); }
	v_fmamk_f32 v178, v167, 0x39800000, v185
	v_rsq_f32_e32 v178, v178
	s_nop 0
	v_mul_f32_e32 v178, 0x41e1c71c, v178
	v_lshlrev_b32_e32 v170, 16, v228
	v_and_b32_e32 v171, 0xffff0000, v228
	v_lshlrev_b32_e32 v172, 16, v229
	v_and_b32_e32 v173, 0xffff0000, v229
	v_add_f32_e32 v46, v46, v170
	v_add_f32_e32 v47, v47, v171
	v_add_f32_e32 v48, v48, v172
	v_add_f32_e32 v49, v49, v173
	v_cvt_pk_bf16_f32 v244, v46, v47
	v_cvt_pk_bf16_f32 v245, v48, v49
	v_mul_f32_e32 v174, v178, v46
	v_mul_f32_e32 v175, v178, v47
	v_mul_f32_e32 v176, v178, v48
	v_mul_f32_e32 v177, v178, v49
	v_rndne_f32_e32 v174, v174
	v_rndne_f32_e32 v175, v175
	v_rndne_f32_e32 v176, v176
	v_rndne_f32_e32 v177, v177
	v_med3_f32 v174, v174, s50, v186
	v_med3_f32 v175, v175, s50, v186
	v_med3_f32 v176, v176, s50, v186
	v_med3_f32 v177, v177, s50, v186
	v_cvt_i32_f32_e32 v174, v174
	v_cvt_i32_f32_e32 v175, v175
	v_cvt_i32_f32_e32 v176, v176
	v_cvt_i32_f32_e32 v177, v177
	v_and_b32_e32 v174, 0xff, v174
	v_and_b32_e32 v175, 0xff, v175
	v_and_b32_e32 v176, 0xff, v176
	v_lshl_or_b32 v174, v175, 8, v174
	v_lshl_or_b32 v174, v176, 16, v174
	v_lshl_or_b32 v248, v177, 24, v174
	v_lshlrev_b32_e32 v170, 16, v230
	v_and_b32_e32 v171, 0xffff0000, v230
	v_lshlrev_b32_e32 v172, 16, v231
	v_and_b32_e32 v173, 0xffff0000, v231
	v_add_f32_e32 v42, v42, v170
	v_add_f32_e32 v43, v43, v171
	v_add_f32_e32 v44, v44, v172
	v_add_f32_e32 v45, v45, v173
	v_cvt_pk_bf16_f32 v246, v42, v43
	v_cvt_pk_bf16_f32 v247, v44, v45
	v_mul_f32_e32 v174, v178, v42
	v_mul_f32_e32 v175, v178, v43
	v_mul_f32_e32 v176, v178, v44
	v_mul_f32_e32 v177, v178, v45
	v_rndne_f32_e32 v174, v174
	v_rndne_f32_e32 v175, v175
	v_rndne_f32_e32 v176, v176
	v_rndne_f32_e32 v177, v177
	v_med3_f32 v174, v174, s50, v186
	v_med3_f32 v175, v175, s50, v186
	v_med3_f32 v176, v176, s50, v186
	v_med3_f32 v177, v177, s50, v186
	v_cvt_i32_f32_e32 v174, v174
	v_cvt_i32_f32_e32 v175, v175
	v_cvt_i32_f32_e32 v176, v176
	v_cvt_i32_f32_e32 v177, v177
	v_and_b32_e32 v174, 0xff, v174
	v_and_b32_e32 v175, 0xff, v175
	v_and_b32_e32 v176, 0xff, v176
	v_lshl_or_b32 v174, v175, 8, v174
	v_lshl_or_b32 v174, v176, 16, v174
	v_lshl_or_b32 v249, v177, 24, v174
	global_store_dwordx4 v251, v[244:247], s[86:87]
	global_store_dwordx2 v252, v[248:249], s[88:89]
	s_nop 0
	v_lshlrev_b32_e32 v170, 16, v232
	v_and_b32_e32 v171, 0xffff0000, v232
	v_lshlrev_b32_e32 v172, 16, v233
	v_and_b32_e32 v173, 0xffff0000, v233
	v_add_f32_e32 v38, v38, v170
	v_add_f32_e32 v39, v39, v171
	v_add_f32_e32 v40, v40, v172
	v_add_f32_e32 v41, v41, v173
	v_cvt_pk_bf16_f32 v244, v38, v39
	v_cvt_pk_bf16_f32 v245, v40, v41
	v_mul_f32_e32 v174, v178, v38
	v_mul_f32_e32 v175, v178, v39
	v_mul_f32_e32 v176, v178, v40
	v_mul_f32_e32 v177, v178, v41
	v_rndne_f32_e32 v174, v174
	v_rndne_f32_e32 v175, v175
	v_rndne_f32_e32 v176, v176
	v_rndne_f32_e32 v177, v177
	v_med3_f32 v174, v174, s50, v186
	v_med3_f32 v175, v175, s50, v186
	v_med3_f32 v176, v176, s50, v186
	v_med3_f32 v177, v177, s50, v186
	v_cvt_i32_f32_e32 v174, v174
	v_cvt_i32_f32_e32 v175, v175
	v_cvt_i32_f32_e32 v176, v176
	v_cvt_i32_f32_e32 v177, v177
	v_and_b32_e32 v174, 0xff, v174
	v_and_b32_e32 v175, 0xff, v175
	v_and_b32_e32 v176, 0xff, v176
	v_lshl_or_b32 v174, v175, 8, v174
	v_lshl_or_b32 v174, v176, 16, v174
	v_lshl_or_b32 v248, v177, 24, v174
	v_lshlrev_b32_e32 v170, 16, v234
	v_and_b32_e32 v171, 0xffff0000, v234
	v_lshlrev_b32_e32 v172, 16, v235
	v_and_b32_e32 v173, 0xffff0000, v235
	v_add_f32_e32 v34, v34, v170
	v_add_f32_e32 v35, v35, v171
	v_add_f32_e32 v36, v36, v172
	v_add_f32_e32 v37, v37, v173
	v_cvt_pk_bf16_f32 v246, v34, v35
	v_cvt_pk_bf16_f32 v247, v36, v37
	v_mul_f32_e32 v174, v178, v34
	v_mul_f32_e32 v175, v178, v35
	v_mul_f32_e32 v176, v178, v36
	v_mul_f32_e32 v177, v178, v37
	v_rndne_f32_e32 v174, v174
	v_rndne_f32_e32 v175, v175
	v_rndne_f32_e32 v176, v176
	v_rndne_f32_e32 v177, v177
	v_med3_f32 v174, v174, s50, v186
	v_med3_f32 v175, v175, s50, v186
	v_med3_f32 v176, v176, s50, v186
	v_med3_f32 v177, v177, s50, v186
	v_cvt_i32_f32_e32 v174, v174
	v_cvt_i32_f32_e32 v175, v175
	v_cvt_i32_f32_e32 v176, v176
	v_cvt_i32_f32_e32 v177, v177
	v_and_b32_e32 v174, 0xff, v174
	v_and_b32_e32 v175, 0xff, v175
	v_and_b32_e32 v176, 0xff, v176
	v_lshl_or_b32 v174, v175, 8, v174
	v_lshl_or_b32 v174, v176, 16, v174
	v_lshl_or_b32 v249, v177, 24, v174
	global_store_dwordx4 v251, v[244:247], s[86:87] offset:256
	global_store_dwordx2 v252, v[248:249], s[88:89] offset:128
	s_nop 0
	s_add_u32 s86, s86, 0x20000
	s_addc_u32 s87, s87, 0
	s_add_u32 s88, s88, 0x10000
	s_addc_u32 s89, s89, 0
	s_waitcnt vmcnt(27)
; __device__ __forceinline__ u32x4 pack8(const f32x4 a, const f32x4 b) { u32x4 w; w.x = cvt_pk_bf16(a[0], a[1]); w.y = cvt_pk_bf16(a[2], a[3]); w.z = cvt_pk_bf16(b[0], b[1]); w.w = cvt_pk_bf16(b[2], b[3]); return w; }
;     __device__ __forceinline__ void operator()(const f32x4 (&acc)[2][2][4][2], const pg8::Unit& u, int wr, int wc, int fr, int fq) const {
;     ...
;                 for (int bj = 0; bj < 2; ++bj) hr[m][bj] = *(const u32x4*)(HB + (size_t)(row0 + ai * 128 + m * 16) * DM + col0 + bj * 128); }
; #pragma unroll
;             for (int m = 0; m < 4; ++m) { const float iq = (127.f / QCLIP) * rsqrtf(q1v[m] * (1.f / DM) + EPS);
; #pragma unroll
;                 for (int bj = 0; bj < 2; ++bj) { float hv[8]; unpack8(hr[m][bj], hv); const size_t off = (size_t)(row0 + ai * 128 + m * 16) * DM + col0 + bj * 128;
;                     f32x4 h0 = acc[ai][bj][m][0], h1 = acc[ai][bj][m][1];
; #pragma unroll
;                     for (int e = 0; e < 4; ++e) { h0[e] += hv[e]; h1[e] += hv[4 + e]; }
;                     *(u32x4*)(HB + off) = pack8(h0, h1);
;                     f32x4 q0, q1;
; #pragma unroll
;                     for (int ee = 0; ee < 4; ++ee) { q0[ee] = fminf(fmaxf(rintf(h0[ee] * iq), -127.f), 127.f); q1[ee] = fminf(fmaxf(rintf(h1[ee] * iq), -127.f), 127.f); }
;                     *(u32x2*)(HQ + off) = pack8_i8(q0, q1); } }
;             asm volatile("" ::: "memory"); }
	v_fmamk_f32 v178, v168, 0x39800000, v185
	v_rsq_f32_e32 v178, v178
	s_nop 0
	v_mul_f32_e32 v178, 0x41e1c71c, v178
	v_lshlrev_b32_e32 v170, 16, v236
	v_and_b32_e32 v171, 0xffff0000, v236
	v_lshlrev_b32_e32 v172, 16, v237
	v_and_b32_e32 v173, 0xffff0000, v237
	v_add_f32_e32 v30, v30, v170
	v_add_f32_e32 v31, v31, v171
	v_add_f32_e32 v32, v32, v172
	v_add_f32_e32 v33, v33, v173
	v_cvt_pk_bf16_f32 v244, v30, v31
	v_cvt_pk_bf16_f32 v245, v32, v33
	v_mul_f32_e32 v174, v178, v30
	v_mul_f32_e32 v175, v178, v31
	v_mul_f32_e32 v176, v178, v32
	v_mul_f32_e32 v177, v178, v33
	v_rndne_f32_e32 v174, v174
	v_rndne_f32_e32 v175, v175
	v_rndne_f32_e32 v176, v176
	v_rndne_f32_e32 v177, v177
	v_med3_f32 v174, v174, s50, v186
	v_med3_f32 v175, v175, s50, v186
	v_med3_f32 v176, v176, s50, v186
	v_med3_f32 v177, v177, s50, v186
	v_cvt_i32_f32_e32 v174, v174
	v_cvt_i32_f32_e32 v175, v175
	v_cvt_i32_f32_e32 v176, v176
	v_cvt_i32_f32_e32 v177, v177
	v_and_b32_e32 v174, 0xff, v174
	v_and_b32_e32 v175, 0xff, v175
	v_and_b32_e32 v176, 0xff, v176
	v_lshl_or_b32 v174, v175, 8, v174
	v_lshl_or_b32 v174, v176, 16, v174
	v_lshl_or_b32 v248, v177, 24, v174
	v_lshlrev_b32_e32 v170, 16, v238
	v_and_b32_e32 v171, 0xffff0000, v238
	v_lshlrev_b32_e32 v172, 16, v239
	v_and_b32_e32 v173, 0xffff0000, v239
	v_add_f32_e32 v26, v26, v170
	v_add_f32_e32 v27, v27, v171
	v_add_f32_e32 v28, v28, v172
	v_add_f32_e32 v29, v29, v173
	v_cvt_pk_bf16_f32 v246, v26, v27
	v_cvt_pk_bf16_f32 v247, v28, v29
	v_mul_f32_e32 v174, v178, v26
	v_mul_f32_e32 v175, v178, v27
	v_mul_f32_e32 v176, v178, v28
	v_mul_f32_e32 v177, v178, v29
	v_rndne_f32_e32 v174, v174
	v_rndne_f32_e32 v175, v175
	v_rndne_f32_e32 v176, v176
	v_rndne_f32_e32 v177, v177
	v_med3_f32 v174, v174, s50, v186
	v_med3_f32 v175, v175, s50, v186
	v_med3_f32 v176, v176, s50, v186
	v_med3_f32 v177, v177, s50, v186
	v_cvt_i32_f32_e32 v174, v174
	v_cvt_i32_f32_e32 v175, v175
	v_cvt_i32_f32_e32 v176, v176
	v_cvt_i32_f32_e32 v177, v177
	v_and_b32_e32 v174, 0xff, v174
	v_and_b32_e32 v175, 0xff, v175
	v_and_b32_e32 v176, 0xff, v176
	v_lshl_or_b32 v174, v175, 8, v174
	v_lshl_or_b32 v174, v176, 16, v174
	v_lshl_or_b32 v249, v177, 24, v174
	global_store_dwordx4 v251, v[244:247], s[86:87]
	global_store_dwordx2 v252, v[248:249], s[88:89]
	s_nop 0
	v_lshlrev_b32_e32 v170, 16, v240
	v_and_b32_e32 v171, 0xffff0000, v240
	v_lshlrev_b32_e32 v172, 16, v241
	v_and_b32_e32 v173, 0xffff0000, v241
	v_add_f32_e32 v22, v22, v170
	v_add_f32_e32 v23, v23, v171
	v_add_f32_e32 v24, v24, v172
	v_add_f32_e32 v25, v25, v173
	v_cvt_pk_bf16_f32 v244, v22, v23
	v_cvt_pk_bf16_f32 v245, v24, v25
	v_mul_f32_e32 v174, v178, v22
	v_mul_f32_e32 v175, v178, v23
	v_mul_f32_e32 v176, v178, v24
	v_mul_f32_e32 v177, v178, v25
	v_rndne_f32_e32 v174, v174
	v_rndne_f32_e32 v175, v175
	v_rndne_f32_e32 v176, v176
	v_rndne_f32_e32 v177, v177
	v_med3_f32 v174, v174, s50, v186
	v_med3_f32 v175, v175, s50, v186
	v_med3_f32 v176, v176, s50, v186
	v_med3_f32 v177, v177, s50, v186
	v_cvt_i32_f32_e32 v174, v174
	v_cvt_i32_f32_e32 v175, v175
	v_cvt_i32_f32_e32 v176, v176
	v_cvt_i32_f32_e32 v177, v177
	v_and_b32_e32 v174, 0xff, v174
	v_and_b32_e32 v175, 0xff, v175
	v_and_b32_e32 v176, 0xff, v176
	v_lshl_or_b32 v174, v175, 8, v174
	v_lshl_or_b32 v174, v176, 16, v174
	v_lshl_or_b32 v248, v177, 24, v174
	v_lshlrev_b32_e32 v170, 16, v242
	v_and_b32_e32 v171, 0xffff0000, v242
	v_lshlrev_b32_e32 v172, 16, v243
	v_and_b32_e32 v173, 0xffff0000, v243
	v_add_f32_e32 v18, v18, v170
	v_add_f32_e32 v19, v19, v171
	v_add_f32_e32 v20, v20, v172
	v_add_f32_e32 v21, v21, v173
	v_cvt_pk_bf16_f32 v246, v18, v19
	v_cvt_pk_bf16_f32 v247, v20, v21
	v_mul_f32_e32 v174, v178, v18
	v_mul_f32_e32 v175, v178, v19
	v_mul_f32_e32 v176, v178, v20
	v_mul_f32_e32 v177, v178, v21
	v_rndne_f32_e32 v174, v174
	v_rndne_f32_e32 v175, v175
	v_rndne_f32_e32 v176, v176
	v_rndne_f32_e32 v177, v177
	v_med3_f32 v174, v174, s50, v186
	v_med3_f32 v175, v175, s50, v186
	v_med3_f32 v176, v176, s50, v186
	v_med3_f32 v177, v177, s50, v186
	v_cvt_i32_f32_e32 v174, v174
	v_cvt_i32_f32_e32 v175, v175
	v_cvt_i32_f32_e32 v176, v176
	v_cvt_i32_f32_e32 v177, v177
	v_and_b32_e32 v174, 0xff, v174
	v_and_b32_e32 v175, 0xff, v175
	v_and_b32_e32 v176, 0xff, v176
	v_lshl_or_b32 v174, v175, 8, v174
	v_lshl_or_b32 v174, v176, 16, v174
	v_lshl_or_b32 v249, v177, 24, v174
	global_store_dwordx4 v251, v[244:247], s[86:87] offset:256
	global_store_dwordx2 v252, v[248:249], s[88:89] offset:128
	s_nop 0
	s_add_u32 s86, s86, 0x20000
	s_addc_u32 s87, s87, 0
	s_add_u32 s88, s88, 0x10000
	s_addc_u32 s89, s89, 0
	s_waitcnt vmcnt(24)
; __device__ __forceinline__ u32x4 pack8(const f32x4 a, const f32x4 b) { u32x4 w; w.x = cvt_pk_bf16(a[0], a[1]); w.y = cvt_pk_bf16(a[2], a[3]); w.z = cvt_pk_bf16(b[0], b[1]); w.w = cvt_pk_bf16(b[2], b[3]); return w; }
;     __device__ __forceinline__ void operator()(const f32x4 (&acc)[2][2][4][2], const pg8::Unit& u, int wr, int wc, int fr, int fq) const {
;     ...
;                 for (int bj = 0; bj < 2; ++bj) hr[m][bj] = *(const u32x4*)(HB + (size_t)(row0 + ai * 128 + m * 16) * DM + col0 + bj * 128); }
; #pragma unroll
;             for (int m = 0; m < 4; ++m) { const float iq = (127.f / QCLIP) * rsqrtf(q1v[m] * (1.f / DM) + EPS);
; #pragma unroll
;                 for (int bj = 0; bj < 2; ++bj) { float hv[8]; unpack8(hr[m][bj], hv); const size_t off = (size_t)(row0 + ai * 128 + m * 16) * DM + col0 + bj * 128;
;                     f32x4 h0 = acc[ai][bj][m][0], h1 = acc[ai][bj][m][1];
; #pragma unroll
;                     for (int e = 0; e < 4; ++e) { h0[e] += hv[e]; h1[e] += hv[4 + e]; }
;                     *(u32x4*)(HB + off) = pack8(h0, h1);
;                     f32x4 q0, q1;
; #pragma unroll
;                     for (int ee = 0; ee < 4; ++ee) { q0[ee] = fminf(fmaxf(rintf(h0[ee] * iq), -127.f), 127.f); q1[ee] = fminf(fmaxf(rintf(h1[ee] * iq), -127.f), 127.f); }
;                     *(u32x2*)(HQ + off) = pack8_i8(q0, q1); } }
;             asm volatile("" ::: "memory"); }
	v_fmamk_f32 v178, v162, 0x39800000, v185
	v_rsq_f32_e32 v178, v178
	s_nop 0
	v_mul_f32_e32 v178, 0x41e1c71c, v178
	v_lshlrev_b32_e32 v170, 16, v188
	v_and_b32_e32 v171, 0xffff0000, v188
	v_lshlrev_b32_e32 v172, 16, v189
	v_and_b32_e32 v173, 0xffff0000, v189
	v_add_f32_e32 v14, v14, v170
	v_add_f32_e32 v15, v15, v171
	v_add_f32_e32 v16, v16, v172
	v_add_f32_e32 v17, v17, v173
	v_cvt_pk_bf16_f32 v244, v14, v15
	v_cvt_pk_bf16_f32 v245, v16, v17
	v_mul_f32_e32 v174, v178, v14
	v_mul_f32_e32 v175, v178, v15
	v_mul_f32_e32 v176, v178, v16
	v_mul_f32_e32 v177, v178, v17
	v_rndne_f32_e32 v174, v174
	v_rndne_f32_e32 v175, v175
	v_rndne_f32_e32 v176, v176
	v_rndne_f32_e32 v177, v177
	v_med3_f32 v174, v174, s50, v186
	v_med3_f32 v175, v175, s50, v186
	v_med3_f32 v176, v176, s50, v186
	v_med3_f32 v177, v177, s50, v186
	v_cvt_i32_f32_e32 v174, v174
	v_cvt_i32_f32_e32 v175, v175
	v_cvt_i32_f32_e32 v176, v176
	v_cvt_i32_f32_e32 v177, v177
	v_and_b32_e32 v174, 0xff, v174
	v_and_b32_e32 v175, 0xff, v175
	v_and_b32_e32 v176, 0xff, v176
	v_lshl_or_b32 v174, v175, 8, v174
	v_lshl_or_b32 v174, v176, 16, v174
	v_lshl_or_b32 v248, v177, 24, v174
	v_lshlrev_b32_e32 v170, 16, v190
	v_and_b32_e32 v171, 0xffff0000, v190
	v_lshlrev_b32_e32 v172, 16, v191
	v_and_b32_e32 v173, 0xffff0000, v191
	v_add_f32_e32 v10, v10, v170
	v_add_f32_e32 v11, v11, v171
	v_add_f32_e32 v12, v12, v172
	v_add_f32_e32 v13, v13, v173
	v_cvt_pk_bf16_f32 v246, v10, v11
	v_cvt_pk_bf16_f32 v247, v12, v13
	v_mul_f32_e32 v174, v178, v10
	v_mul_f32_e32 v175, v178, v11
	v_mul_f32_e32 v176, v178, v12
	v_mul_f32_e32 v177, v178, v13
	v_rndne_f32_e32 v174, v174
	v_rndne_f32_e32 v175, v175
	v_rndne_f32_e32 v176, v176
	v_rndne_f32_e32 v177, v177
	v_med3_f32 v174, v174, s50, v186
	v_med3_f32 v175, v175, s50, v186
	v_med3_f32 v176, v176, s50, v186
	v_med3_f32 v177, v177, s50, v186
	v_cvt_i32_f32_e32 v174, v174
	v_cvt_i32_f32_e32 v175, v175
	v_cvt_i32_f32_e32 v176, v176
	v_cvt_i32_f32_e32 v177, v177
	v_and_b32_e32 v174, 0xff, v174
	v_and_b32_e32 v175, 0xff, v175
	v_and_b32_e32 v176, 0xff, v176
	v_lshl_or_b32 v174, v175, 8, v174
	v_lshl_or_b32 v174, v176, 16, v174
	v_lshl_or_b32 v249, v177, 24, v174
	global_store_dwordx4 v251, v[244:247], s[86:87]
	global_store_dwordx2 v252, v[248:249], s[88:89]
	s_nop 0
	v_lshlrev_b32_e32 v170, 16, v192
	v_and_b32_e32 v171, 0xffff0000, v192
	v_lshlrev_b32_e32 v172, 16, v193
	v_and_b32_e32 v173, 0xffff0000, v193
	v_add_f32_e32 v6, v6, v170
	v_add_f32_e32 v7, v7, v171
	v_add_f32_e32 v8, v8, v172
	v_add_f32_e32 v9, v9, v173
	v_cvt_pk_bf16_f32 v244, v6, v7
	v_cvt_pk_bf16_f32 v245, v8, v9
	v_mul_f32_e32 v174, v178, v6
	v_mul_f32_e32 v175, v178, v7
	v_mul_f32_e32 v176, v178, v8
	v_mul_f32_e32 v177, v178, v9
	v_rndne_f32_e32 v174, v174
	v_rndne_f32_e32 v175, v175
	v_rndne_f32_e32 v176, v176
	v_rndne_f32_e32 v177, v177
	v_med3_f32 v174, v174, s50, v186
	v_med3_f32 v175, v175, s50, v186
	v_med3_f32 v176, v176, s50, v186
	v_med3_f32 v177, v177, s50, v186
	v_cvt_i32_f32_e32 v174, v174
	v_cvt_i32_f32_e32 v175, v175
	v_cvt_i32_f32_e32 v176, v176
	v_cvt_i32_f32_e32 v177, v177
	v_and_b32_e32 v174, 0xff, v174
	v_and_b32_e32 v175, 0xff, v175
	v_and_b32_e32 v176, 0xff, v176
	v_lshl_or_b32 v174, v175, 8, v174
	v_lshl_or_b32 v174, v176, 16, v174
	v_lshl_or_b32 v248, v177, 24, v174
	v_lshlrev_b32_e32 v170, 16, v194
	v_and_b32_e32 v171, 0xffff0000, v194
	v_lshlrev_b32_e32 v172, 16, v195
	v_and_b32_e32 v173, 0xffff0000, v195
	v_add_f32_e32 v2, v2, v170
	v_add_f32_e32 v3, v3, v171
	v_add_f32_e32 v4, v4, v172
	v_add_f32_e32 v5, v5, v173
	v_cvt_pk_bf16_f32 v246, v2, v3
	v_cvt_pk_bf16_f32 v247, v4, v5
	v_mul_f32_e32 v174, v178, v2
	v_mul_f32_e32 v175, v178, v3
	v_mul_f32_e32 v176, v178, v4
	v_mul_f32_e32 v177, v178, v5
	v_rndne_f32_e32 v174, v174
	v_rndne_f32_e32 v175, v175
	v_rndne_f32_e32 v176, v176
	v_rndne_f32_e32 v177, v177
	v_med3_f32 v174, v174, s50, v186
	v_med3_f32 v175, v175, s50, v186
	v_med3_f32 v176, v176, s50, v186
	v_med3_f32 v177, v177, s50, v186
	v_cvt_i32_f32_e32 v174, v174
	v_cvt_i32_f32_e32 v175, v175
	v_cvt_i32_f32_e32 v176, v176
	v_cvt_i32_f32_e32 v177, v177
	v_and_b32_e32 v174, 0xff, v174
	v_and_b32_e32 v175, 0xff, v175
	v_and_b32_e32 v176, 0xff, v176
	v_lshl_or_b32 v174, v175, 8, v174
	v_lshl_or_b32 v174, v176, 16, v174
	v_lshl_or_b32 v249, v177, 24, v174
	global_store_dwordx4 v251, v[244:247], s[86:87] offset:256
	global_store_dwordx2 v252, v[248:249], s[88:89] offset:128
	s_nop 0
	s_nop 1
	s_and_b64 vcc, exec, s[6:7]
	s_mov_b64 s[6:7], -1
	s_cbranch_vccnz .LBB0_1364
	s_andn2_b64 vcc, exec, s[12:13]
	s_cbranch_vccnz .LBB0_1363
	s_barrier
	s_branch .LBB0_1363
